# convert_uv: hand-written quantise+pack (73 fewer instructions per table row)
# baseline (speedup 1.0000x reference)
; __device__ void convert_uv(const Params& p, int part, int nparts) {
;     ...
;     float ss = 0.f;
; #pragma unroll
;     for (int q = 0; q < 8; ++q) {
;       f32x4 t = *(const f32x4*)(src + q * 4);
;       if (!isv) t *= *(const f32x4*)(p.norm_ffn_w + lane * 32 + q * 4);
; #pragma unroll
;       for (int k = 0; k < 4; ++k) {
;         vals[q * 4 + k] = t[k];
;         ss += t[k] * t[k];
;       }
;     }
;     ss = wave_sum(ss);
.LBB0_1121:
	s_or_b64 exec, exec, s[0:1]
	v_mul_f32_e32 v44, v27, v27
	v_fmac_f32_e32 v44, v26, v26
	v_fmac_f32_e32 v44, v28, v28
	v_fmac_f32_e32 v44, v29, v29
	v_fmac_f32_e32 v44, v30, v30
	v_fmac_f32_e32 v44, v31, v31
	v_fmac_f32_e32 v44, v32, v32
	v_fmac_f32_e32 v44, v33, v33
	v_fmac_f32_e32 v44, v18, v18
	v_fmac_f32_e32 v44, v19, v19
	v_fmac_f32_e32 v44, v20, v20
	v_fmac_f32_e32 v44, v21, v21
	v_fmac_f32_e32 v44, v22, v22
	v_fmac_f32_e32 v44, v23, v23
	v_fmac_f32_e32 v44, v24, v24
	v_fmac_f32_e32 v44, v25, v25
	v_fmac_f32_e32 v44, v10, v10
	v_fmac_f32_e32 v44, v11, v11
	v_fmac_f32_e32 v44, v12, v12
	v_fmac_f32_e32 v44, v13, v13
	v_fmac_f32_e32 v44, v14, v14
	v_fmac_f32_e32 v44, v15, v15
	v_fmac_f32_e32 v44, v16, v16
	v_fmac_f32_e32 v44, v17, v17
	v_fmac_f32_e32 v44, v2, v2
	v_fmac_f32_e32 v44, v3, v3
	v_fmac_f32_e32 v44, v4, v4
	v_fmac_f32_e32 v44, v5, v5
	v_pk_mul_f32 v[42:43], v[6:7], v[6:7]
	v_pk_mul_f32 v[40:41], v[8:9], v[8:9]
	v_add_f32_e32 v42, v44, v42
	v_add_f32_e32 v42, v43, v42
	v_add_f32_e32 v40, v40, v42
	v_add_f32_e32 v40, v41, v40
	ds_bpermute_b32 v41, v106, v40
	s_waitcnt lgkmcnt(0)
	v_add_f32_e32 v40, v40, v41
	ds_bpermute_b32 v41, v107, v40
	s_waitcnt lgkmcnt(0)
	v_add_f32_e32 v40, v40, v41
	ds_bpermute_b32 v41, v108, v40
	s_waitcnt lgkmcnt(0)
	v_add_f32_e32 v40, v40, v41
	ds_bpermute_b32 v41, v109, v40
	s_waitcnt lgkmcnt(0)
	v_add_f32_e32 v40, v40, v41
	ds_bpermute_b32 v41, v110, v40
	s_waitcnt lgkmcnt(0)
	v_add_f32_e32 v40, v40, v41
	ds_bpermute_b32 v41, v111, v40
	s_waitcnt lgkmcnt(0)
; __device__ void convert_uv(const Params& p, int part, int nparts) {
;     ...
;     const float rms = sqrtf(ss * (1.f / 2048.f));
;     const float sc = rms * (2.6f / 7.f);
;     const float inv = sc > 0.f ? 1.f / sc : 0.f;
;     u32x4 o;
; #pragma unroll
;     for (int m = 0; m < 4; ++m) {
;       unsigned w = 0;
; #pragma unroll
;       for (int j = 0; j < 4; ++j) {
;         const float lo = fminf(fmaxf(rintf(vals[m * 8 + j] * inv), -7.f), 7.f);
;         const float hi = fminf(fmaxf(rintf(vals[m * 8 + 4 + j] * inv), -7.f), 7.f);
;         const unsigned bl = isv ? (unsigned)((int)lo + 8) : ((unsigned)(int)lo & 0xfu);
;         const unsigned bh = isv ? (unsigned)((int)hi + 8) : ((unsigned)(int)hi & 0xfu);
;         w |= (bl | (bh << 4)) << (8 * j);
;       }
;       o[m] = w;
;     }
;     *(u32x4*)(tb + (size_t)row * 1024 + lane * 16) = o;
;     if (lane == 0) scales[row] = sc;
	v_add_f32_e32 v40, v40, v41
	v_mul_f32_e32 v40, 0x3a000000, v40
	v_mul_f32_e32 v41, 0x4f800000, v40
	v_cmp_gt_f32_e32 vcc, s63, v40
	s_nop 1
	v_cndmask_b32_e32 v40, v40, v41, vcc
	v_sqrt_f32_e32 v41, v40
	s_nop 0
	v_add_u32_e32 v42, -1, v41
	v_add_u32_e32 v43, 1, v41
	v_fma_f32 v44, -v42, v41, v40
	v_fma_f32 v45, -v43, v41, v40
	v_cmp_ge_f32_e64 s[0:1], 0, v44
	s_nop 1
	v_cndmask_b32_e64 v41, v41, v42, s[0:1]
	v_cmp_lt_f32_e64 s[0:1], 0, v45
	s_nop 1
	v_cndmask_b32_e64 v41, v41, v43, s[0:1]
	v_mul_f32_e32 v42, 0x37800000, v41
	v_cndmask_b32_e32 v41, v41, v42, vcc
	v_cmp_class_f32_e32 vcc, v40, v119
	s_nop 1
	v_cndmask_b32_e32 v40, v41, v40, vcc
	v_mul_f32_e32 v40, 0x3ebe2be2, v40
	v_div_scale_f32 v41, s[0:1], v40, v40, 1.0
	v_rcp_f32_e32 v42, v41
	v_div_scale_f32 v43, vcc, 1.0, v40, 1.0
	v_fma_f32 v44, -v41, v42, 1.0
	v_fmac_f32_e32 v42, v44, v42
	v_mul_f32_e32 v44, v43, v42
	v_fma_f32 v45, -v41, v44, v43
	v_fmac_f32_e32 v44, v45, v42
	v_fma_f32 v41, -v41, v44, v43
	v_div_fmas_f32 v41, v41, v42, v44
	v_div_fixup_f32 v41, v41, v40, 1.0
	v_cmp_lt_f32_e32 vcc, 0, v40
	s_nop 1
	v_cndmask_b32_e32 v41, 0, v41, vcc
	v_mul_f32_e32 v26, v26, v41
	v_rndne_f32_e32 v26, v26
	v_med3_f32 v26, v26, s64, v120
	v_cvt_i32_f32_e32 v26, v26
	v_add_u32_e32 v26, 8, v26
	v_mul_f32_e32 v27, v27, v41
	v_rndne_f32_e32 v27, v27
	v_med3_f32 v27, v27, s64, v120
	v_cvt_i32_f32_e32 v27, v27
	v_add_lshl_u32 v27, v27, 8, 8
	v_mul_f32_e32 v28, v28, v41
	v_rndne_f32_e32 v28, v28
	v_med3_f32 v28, v28, s64, v120
	v_cvt_i32_f32_e32 v28, v28
	v_add_lshl_u32 v28, v28, 8, 16
	v_mul_f32_e32 v29, v29, v41
	v_rndne_f32_e32 v29, v29
	v_med3_f32 v29, v29, s64, v120
	v_cvt_i32_f32_e32 v29, v29
	v_add_lshl_u32 v29, v29, 8, 24
	v_mul_f32_e32 v30, v30, v41
	v_rndne_f32_e32 v30, v30
	v_med3_f32 v30, v30, s64, v120
	v_cvt_i32_f32_e32 v30, v30
	v_add_lshl_u32 v30, v30, 8, 4
	v_mul_f32_e32 v31, v31, v41
	v_rndne_f32_e32 v31, v31
	v_med3_f32 v31, v31, s64, v120
	v_cvt_i32_f32_e32 v31, v31
	v_add_lshl_u32 v31, v31, 8, 12
	v_mul_f32_e32 v32, v32, v41
	v_rndne_f32_e32 v32, v32
	v_med3_f32 v32, v32, s64, v120
	v_cvt_i32_f32_e32 v32, v32
	v_add_lshl_u32 v32, v32, 8, 20
	v_mul_f32_e32 v33, v33, v41
	v_rndne_f32_e32 v33, v33
	v_med3_f32 v33, v33, s64, v120
	v_cvt_i32_f32_e32 v33, v33
	v_add_lshl_u32 v33, v33, 8, 28
	v_or3_b32 v42, v26, v27, v28
	v_or3_b32 v42, v42, v29, v30
	v_or3_b32 v42, v42, v31, v32
	v_or_b32_e32 v42, v42, v33
	v_mul_f32_e32 v18, v18, v41
	v_rndne_f32_e32 v18, v18
	v_med3_f32 v18, v18, s64, v120
	v_cvt_i32_f32_e32 v18, v18
	v_add_u32_e32 v18, 8, v18
	v_mul_f32_e32 v19, v19, v41
	v_rndne_f32_e32 v19, v19
	v_med3_f32 v19, v19, s64, v120
	v_cvt_i32_f32_e32 v19, v19
	v_add_lshl_u32 v19, v19, 8, 8
	v_mul_f32_e32 v20, v20, v41
	v_rndne_f32_e32 v20, v20
	v_med3_f32 v20, v20, s64, v120
	v_cvt_i32_f32_e32 v20, v20
	v_add_lshl_u32 v20, v20, 8, 16
	v_mul_f32_e32 v21, v21, v41
	v_rndne_f32_e32 v21, v21
	v_med3_f32 v21, v21, s64, v120
	v_cvt_i32_f32_e32 v21, v21
	v_add_lshl_u32 v21, v21, 8, 24
	v_mul_f32_e32 v22, v22, v41
	v_rndne_f32_e32 v22, v22
	v_med3_f32 v22, v22, s64, v120
	v_cvt_i32_f32_e32 v22, v22
	v_add_lshl_u32 v22, v22, 8, 4
	v_mul_f32_e32 v23, v23, v41
	v_rndne_f32_e32 v23, v23
	v_med3_f32 v23, v23, s64, v120
	v_cvt_i32_f32_e32 v23, v23
	v_add_lshl_u32 v23, v23, 8, 12
	v_mul_f32_e32 v24, v24, v41
	v_rndne_f32_e32 v24, v24
	v_med3_f32 v24, v24, s64, v120
	v_cvt_i32_f32_e32 v24, v24
	v_add_lshl_u32 v24, v24, 8, 20
	v_mul_f32_e32 v25, v25, v41
	v_rndne_f32_e32 v25, v25
	v_med3_f32 v25, v25, s64, v120
	v_cvt_i32_f32_e32 v25, v25
	v_add_lshl_u32 v25, v25, 8, 28
	v_or3_b32 v43, v18, v19, v20
	v_or3_b32 v43, v43, v21, v22
	v_or3_b32 v43, v43, v23, v24
	v_or_b32_e32 v43, v43, v25
	v_mul_f32_e32 v10, v10, v41
	v_rndne_f32_e32 v10, v10
	v_med3_f32 v10, v10, s64, v120
	v_cvt_i32_f32_e32 v10, v10
	v_add_u32_e32 v10, 8, v10
	v_mul_f32_e32 v11, v11, v41
	v_rndne_f32_e32 v11, v11
	v_med3_f32 v11, v11, s64, v120
	v_cvt_i32_f32_e32 v11, v11
	v_add_lshl_u32 v11, v11, 8, 8
	v_mul_f32_e32 v12, v12, v41
	v_rndne_f32_e32 v12, v12
	v_med3_f32 v12, v12, s64, v120
	v_cvt_i32_f32_e32 v12, v12
	v_add_lshl_u32 v12, v12, 8, 16
	v_mul_f32_e32 v13, v13, v41
	v_rndne_f32_e32 v13, v13
	v_med3_f32 v13, v13, s64, v120
	v_cvt_i32_f32_e32 v13, v13
	v_add_lshl_u32 v13, v13, 8, 24
	v_mul_f32_e32 v14, v14, v41
	v_rndne_f32_e32 v14, v14
	v_med3_f32 v14, v14, s64, v120
	v_cvt_i32_f32_e32 v14, v14
	v_add_lshl_u32 v14, v14, 8, 4
	v_mul_f32_e32 v15, v15, v41
	v_rndne_f32_e32 v15, v15
	v_med3_f32 v15, v15, s64, v120
	v_cvt_i32_f32_e32 v15, v15
	v_add_lshl_u32 v15, v15, 8, 12
	v_mul_f32_e32 v16, v16, v41
	v_rndne_f32_e32 v16, v16
	v_med3_f32 v16, v16, s64, v120
	v_cvt_i32_f32_e32 v16, v16
	v_add_lshl_u32 v16, v16, 8, 20
	v_mul_f32_e32 v17, v17, v41
	v_rndne_f32_e32 v17, v17
	v_med3_f32 v17, v17, s64, v120
	v_cvt_i32_f32_e32 v17, v17
	v_add_lshl_u32 v17, v17, 8, 28
	v_or3_b32 v44, v10, v11, v12
	v_or3_b32 v44, v44, v13, v14
	v_or3_b32 v44, v44, v15, v16
	v_or_b32_e32 v44, v44, v17
	v_mul_f32_e32 v2, v2, v41
	v_rndne_f32_e32 v2, v2
	v_med3_f32 v2, v2, s64, v120
	v_cvt_i32_f32_e32 v2, v2
	v_add_u32_e32 v2, 8, v2
	v_mul_f32_e32 v3, v3, v41
	v_rndne_f32_e32 v3, v3
	v_med3_f32 v3, v3, s64, v120
	v_cvt_i32_f32_e32 v3, v3
	v_add_lshl_u32 v3, v3, 8, 8
	v_mul_f32_e32 v4, v4, v41
	v_rndne_f32_e32 v4, v4
	v_med3_f32 v4, v4, s64, v120
	v_cvt_i32_f32_e32 v4, v4
	v_add_lshl_u32 v4, v4, 8, 16
	v_mul_f32_e32 v5, v5, v41
	v_rndne_f32_e32 v5, v5
	v_med3_f32 v5, v5, s64, v120
	v_cvt_i32_f32_e32 v5, v5
	v_add_lshl_u32 v5, v5, 8, 24
	v_mul_f32_e32 v6, v6, v41
	v_rndne_f32_e32 v6, v6
	v_med3_f32 v6, v6, s64, v120
	v_cvt_i32_f32_e32 v6, v6
	v_add_lshl_u32 v6, v6, 8, 4
	v_mul_f32_e32 v7, v7, v41
	v_rndne_f32_e32 v7, v7
	v_med3_f32 v7, v7, s64, v120
	v_cvt_i32_f32_e32 v7, v7
	v_add_lshl_u32 v7, v7, 8, 12
	v_mul_f32_e32 v8, v8, v41
	v_rndne_f32_e32 v8, v8
	v_med3_f32 v8, v8, s64, v120
	v_cvt_i32_f32_e32 v8, v8
	v_add_lshl_u32 v8, v8, 8, 20
	v_mul_f32_e32 v9, v9, v41
	v_rndne_f32_e32 v9, v9
	v_med3_f32 v9, v9, s64, v120
	v_cvt_i32_f32_e32 v9, v9
	v_add_lshl_u32 v9, v9, 8, 28
	v_or3_b32 v45, v2, v3, v4
	v_or3_b32 v45, v45, v5, v6
	v_or3_b32 v45, v45, v7, v8
	v_or_b32_e32 v45, v45, v9
	v_mov_b32_e32 v46, 0x88888888
	v_cndmask_b32_e64 v46, v46, 0, s[8:9]
	v_xor_b32_e32 v42, v46, v42
	v_xor_b32_e32 v43, v46, v43
	v_xor_b32_e32 v44, v46, v44
	v_xor_b32_e32 v45, v46, v45
	global_store_dwordx4 v[36:37], v[42:45], off
	s_and_saveexec_b64 s[0:1], s[6:7]
	s_cbranch_execz .LBB0_1111
	global_store_dword v[34:35], v40, off
	s_branch .LBB0_1111
